# v26 + shared-key rope pass dealt to blocks 196-255 (cumsum blocks start at once)
# speedup vs baseline: 1.0175x; 1.0003x over previous
; __device__ __forceinline__ unsigned pk2(float lo, float hi) { f32x2 v = {lo, hi}; bf16x2_t b = __builtin_convertvector(v, bf16x2_t); return __builtin_bit_cast(unsigned, b); }
; __device__ __forceinline__ int my_tid() { int t = threadIdx.x; asm volatile("" : "+v"(t)); return t; }
; __device__ __forceinline__ int my_bx() { int b = blockIdx.x; asm volatile("" : "+s"(b)); return b; }
; __device__ __forceinline__ int my_G() { int g = gridDim.x; asm volatile("" : "+s"(g)); return g; }
; __device__ __forceinline__ void phase_small(const Params& P, int l) {
;     const float* misc = (const float*)(P.ws + WS_MISC); const f32x2* cs = (const f32x2*)(P.ws + WS_CS); bf16_t* kr = (bf16_t*)(P.ws + WS_KR);
;     const int tid = my_tid(), bx = my_bx(), G = my_G();
;     const int rb0 = (G == 256) ? 192 : 0, rnb = G - rb0;
;     for (int idx = (bx - rb0) * 512 + tid; idx < T * 32 && bx >= rb0; idx += rnb * 512) { const int tok = idx >> 5, j = idx & 31;
;         const f32x2 x = *(const f32x2*)(misc + (size_t)tok * 128 + 2 * j); const f32x2 c = cs[idx];
;         *(unsigned*)(kr + (size_t)tok * 64 + 2 * j) = pk2(x[0] * c[0] - x[1] * c[1], x[1] * c[0] + x[0] * c[1]); }
.LBB0_894:
	s_andn2_b64 vcc, exec, s[0:1]
	s_cbranch_vccnz .LBB0_996
	s_mov_b64 s[0:1], s[88:89]
	s_load_dwordx2 s[2:3], s[92:93], 0x90
	v_readlane_b32 s15, v253, 0
	v_mov_b32_e32 v6, v208
	s_mov_b32 s6, 0x40000
	s_waitcnt lgkmcnt(0)
	s_mov_b32 s4, s2
	s_mov_b32 s2, s15
	s_add_u32 s2, s0, 0x2d1e4100
	s_addc_u32 s3, s1, 0
	s_mov_b32 s14, s4
	s_cmpk_eq_i32 s14, 0x100
	s_cselect_b32 s12, 0xc4, 0
	s_sub_i32 s4, s15, s12
	v_lshl_add_u32 v2, s4, 9, v6
	s_cmp_ge_i32 s15, s12
	s_cselect_b64 s[4:5], -1, 0
	v_cmp_gt_i32_e32 vcc, s6, v2
	s_and_b64 s[6:7], s[4:5], vcc
	s_and_saveexec_b64 s[4:5], s[6:7]
	s_cbranch_execz .LBB0_898
	s_add_u32 s6, s0, 0x2d0e4100
	s_addc_u32 s7, s1, 0
	s_sub_i32 s8, s14, s12
	s_lshl_b32 s8, s8, 9
	v_ashrrev_i32_e32 v3, 31, v2
	v_lshl_add_u64 v[4:5], v[2:3], 3, s[0:1]
	s_mov_b64 s[10:11], 0x15a64100
	s_ashr_i32 s9, s8, 31
	v_lshl_add_u64 v[4:5], v[4:5], 0, s[10:11]
	s_lshl_b64 s[10:11], s[8:9], 3
	s_lshl_b32 s9, s14, 10
	s_lshl_b32 s12, s12, 10
	v_lshlrev_b32_e32 v3, 1, v2
	s_sub_i32 s9, s9, s12
	s_mov_b64 s[12:13], 0
